# grid barrier: L1 invalidate + an extra un-waited L2 write-back issued at arrival (leader's write-back kept); plus silu batch, transposed epilogue stores, rowwise-mid fix
# baseline (speedup 1.0000x reference)
; __device__ __forceinline__ unsigned xb_ld(unsigned* p)              { return __hip_atomic_load(p, __ATOMIC_RELAXED, __HIP_MEMORY_SCOPE_AGENT); }
; __device__ __forceinline__ unsigned xb_add(unsigned* p, unsigned v) { return __hip_atomic_fetch_add(p, v, __ATOMIC_RELAXED, __HIP_MEMORY_SCOPE_AGENT); }
; #define XB_SPIN(cond, bar) do { unsigned _sp = 0; while (cond) { __builtin_amdgcn_s_sleep(1); \
;     if ((++_sp & 255u) == 0u) { if (xb_ld(&(bar)[XB_TMO])) break; if (_sp > XB_SPIN_CAP) { atomicAdd(&(bar)[XB_TMO], 1u); break; } } } } while (0)
; __device__ __forceinline__ void xcd_barrier(const XcdBarrier& b) {
;     ...
;         unsigned nloc = b.st[0], nx = b.st[1];
;         if (nloc == 0u) { xcd_barrier_complete(bar, b.x, nloc, nx); b.st[0] = nloc; b.st[1] = nx; }
;         const unsigned old = xb_add(&bar[XB_XSUB(b.x)], 1u);
;         const unsigned gen = old / nloc;
;         if (old + 1u == (gen + 1u) * nloc) {
;             __builtin_amdgcn_fence(__ATOMIC_RELEASE, "agent");
;             asm volatile("s_waitcnt vmcnt(0)" ::: "memory");
;             const unsigned og = xb_add(&bar[XB_TOP], 1u);
;             const unsigned tg = og / nx;
;             if (og + 1u == (tg + 1u) * nx) xb_add(&bar[XB_TOPGEN], 1u);
;             else XB_SPIN(xb_ld(&bar[XB_TOPGEN]) == tg, bar);
;             __builtin_amdgcn_fence(__ATOMIC_ACQUIRE, "agent");
;             xb_add(&bar[XB_XGEN(b.x)], 1u);
;             asm volatile("s_waitcnt vmcnt(0)" ::: "memory");
;         } else {
;             XB_SPIN(xb_ld(&bar[XB_XGEN(b.x)]) == gen, bar);
.LBB0_66:
	s_or_b64 exec, exec, s[14:15]
	buffer_wbl2 sc1
	buffer_inv sc1
	v_cvt_f32_u32_e32 v4, v2
	s_waitcnt vmcnt(2)
	v_readfirstlane_b32 s4, v3
	v_sub_u32_e32 v3, 0, v2
	v_rcp_iflag_f32_e32 v4, v4
	v_add_u32_e32 v5, s4, v1
	v_mul_f32_e32 v4, 0x4f7ffffe, v4
	v_cvt_u32_f32_e32 v4, v4
	v_mul_lo_u32 v1, v3, v4
	v_mul_hi_u32 v1, v4, v1
	v_add_u32_e32 v1, v4, v1
	v_mul_hi_u32 v1, v5, v1
	v_mul_lo_u32 v3, v1, v2
	v_sub_u32_e32 v3, v5, v3
	v_add_u32_e32 v4, 1, v1
	v_cmp_ge_u32_e32 vcc, v3, v2
	s_nop 1
	v_cndmask_b32_e32 v1, v1, v4, vcc
	v_sub_u32_e32 v4, v3, v2
	v_cndmask_b32_e32 v3, v3, v4, vcc
	v_add_u32_e32 v4, 1, v1
	v_cmp_ge_u32_e32 vcc, v3, v2
	v_add_u32_e32 v3, 1, v5
	s_nop 0
	v_cndmask_b32_e32 v1, v1, v4, vcc
	v_mul_lo_u32 v4, v2, v1
	v_add_u32_e32 v2, v4, v2
	v_cmp_ne_u32_e32 vcc, v3, v2
	s_and_saveexec_b64 s[4:5], vcc
	s_xor_b64 s[14:15], exec, s[4:5]
	s_cbranch_execz .LBB0_80
	v_readlane_b32 s4, v245, 18
	s_waitcnt lgkmcnt(0)
	v_mov_b32_e32 v0, 0
	v_readlane_b32 s5, v245, 19
	s_nop 4
	global_load_dword v2, v0, s[4:5] sc1
	s_waitcnt vmcnt(0)
	v_cmp_eq_u32_e32 vcc, v2, v1
	s_and_saveexec_b64 s[18:19], vcc
	s_cbranch_execz .LBB0_79
	s_mov_b32 s4, 1
	s_mov_b64 s[20:21], 0
	s_branch .LBB0_70

; __device__ __forceinline__ unsigned xb_ld(unsigned* p)              { return __hip_atomic_load(p, __ATOMIC_RELAXED, __HIP_MEMORY_SCOPE_AGENT); }
; #define XB_SPIN(cond, bar) do { unsigned _sp = 0; while (cond) { __builtin_amdgcn_s_sleep(1); \
;     if ((++_sp & 255u) == 0u) { if (xb_ld(&(bar)[XB_TMO])) break; if (_sp > XB_SPIN_CAP) { atomicAdd(&(bar)[XB_TMO], 1u); break; } } } } while (0)
; __device__ __forceinline__ void xcd_barrier(const XcdBarrier& b) {
;     ...
;             XB_SPIN(xb_ld(&bar[XB_XGEN(b.x)]) == gen, bar);
;             __builtin_amdgcn_fence(__ATOMIC_ACQUIRE, "agent");
;             asm volatile("s_waitcnt vmcnt(0)" ::: "memory");
.LBB0_79:
	s_or_b64 exec, exec, s[18:19]
	s_waitcnt vmcnt(0)
	s_waitcnt vmcnt(0)

; __device__ __forceinline__ unsigned xb_ld(unsigned* p)              { return __hip_atomic_load(p, __ATOMIC_RELAXED, __HIP_MEMORY_SCOPE_AGENT); }
; __device__ __forceinline__ unsigned xb_add(unsigned* p, unsigned v) { return __hip_atomic_fetch_add(p, v, __ATOMIC_RELAXED, __HIP_MEMORY_SCOPE_AGENT); }
; #define XB_SPIN(cond, bar) do { unsigned _sp = 0; while (cond) { __builtin_amdgcn_s_sleep(1); \
;     if ((++_sp & 255u) == 0u) { if (xb_ld(&(bar)[XB_TMO])) break; if (_sp > XB_SPIN_CAP) { atomicAdd(&(bar)[XB_TMO], 1u); break; } } } } while (0)
; __device__ __forceinline__ void xcd_barrier(const XcdBarrier& b) {
;     ...
;             else XB_SPIN(xb_ld(&bar[XB_TOPGEN]) == tg, bar);
;             __builtin_amdgcn_fence(__ATOMIC_ACQUIRE, "agent");
;             xb_add(&bar[XB_XGEN(b.x)], 1u);
.LBB0_97:
	s_or_b64 exec, exec, s[14:15]
	s_mov_b64 s[14:15], exec
	v_mbcnt_lo_u32_b32 v0, s14, 0
	v_mbcnt_hi_u32_b32 v0, s15, v0
	v_cmp_eq_u32_e32 vcc, 0, v0
	s_waitcnt vmcnt(0)
	s_and_saveexec_b64 s[16:17], vcc
	s_cbranch_execz .LBB0_99
	s_bcnt1_i32_b64 s4, s[14:15]
	v_mov_b32_e32 v1, s4
	v_readlane_b32 s4, v245, 18
	v_mov_b32_e32 v0, 0
	v_readlane_b32 s5, v245, 19
	s_nop 4
	global_atomic_add v0, v1, s[4:5]

; __device__ __forceinline__ unsigned xb_ld(unsigned* p)              { return __hip_atomic_load(p, __ATOMIC_RELAXED, __HIP_MEMORY_SCOPE_AGENT); }
; __device__ __forceinline__ unsigned xb_add(unsigned* p, unsigned v) { return __hip_atomic_fetch_add(p, v, __ATOMIC_RELAXED, __HIP_MEMORY_SCOPE_AGENT); }
; #define XB_SPIN(cond, bar) do { unsigned _sp = 0; while (cond) { __builtin_amdgcn_s_sleep(1); \
;     if ((++_sp & 255u) == 0u) { if (xb_ld(&(bar)[XB_TMO])) break; if (_sp > XB_SPIN_CAP) { atomicAdd(&(bar)[XB_TMO], 1u); break; } } } } while (0)
; __device__ __forceinline__ void xcd_barrier(const XcdBarrier& b) {
;     ...
;         unsigned nloc = b.st[0], nx = b.st[1];
;         if (nloc == 0u) { xcd_barrier_complete(bar, b.x, nloc, nx); b.st[0] = nloc; b.st[1] = nx; }
;         const unsigned old = xb_add(&bar[XB_XSUB(b.x)], 1u);
;         const unsigned gen = old / nloc;
;         if (old + 1u == (gen + 1u) * nloc) {
;             __builtin_amdgcn_fence(__ATOMIC_RELEASE, "agent");
;             asm volatile("s_waitcnt vmcnt(0)" ::: "memory");
;             const unsigned og = xb_add(&bar[XB_TOP], 1u);
;             const unsigned tg = og / nx;
;             if (og + 1u == (tg + 1u) * nx) xb_add(&bar[XB_TOPGEN], 1u);
;             else XB_SPIN(xb_ld(&bar[XB_TOPGEN]) == tg, bar);
;             __builtin_amdgcn_fence(__ATOMIC_ACQUIRE, "agent");
;             xb_add(&bar[XB_XGEN(b.x)], 1u);
;             asm volatile("s_waitcnt vmcnt(0)" ::: "memory");
;         } else {
;             XB_SPIN(xb_ld(&bar[XB_XGEN(b.x)]) == gen, bar);
.LBB0_139:
	s_or_b64 exec, exec, s[8:9]
	buffer_wbl2 sc1
	buffer_inv sc1
	v_cvt_f32_u32_e32 v4, v2
	s_waitcnt vmcnt(2)
	v_readfirstlane_b32 s3, v3
	v_sub_u32_e32 v3, 0, v2
	v_rcp_iflag_f32_e32 v4, v4
	v_add_u32_e32 v5, s3, v1
	v_mul_f32_e32 v4, 0x4f7ffffe, v4
	v_cvt_u32_f32_e32 v4, v4
	v_mul_lo_u32 v1, v3, v4
	v_mul_hi_u32 v1, v4, v1
	v_add_u32_e32 v1, v4, v1
	v_mul_hi_u32 v1, v5, v1
	v_mul_lo_u32 v3, v1, v2
	v_sub_u32_e32 v3, v5, v3
	v_add_u32_e32 v4, 1, v1
	v_cmp_ge_u32_e32 vcc, v3, v2
	s_nop 1
	v_cndmask_b32_e32 v1, v1, v4, vcc
	v_sub_u32_e32 v4, v3, v2
	v_cndmask_b32_e32 v3, v3, v4, vcc
	v_add_u32_e32 v4, 1, v1
	v_cmp_ge_u32_e32 vcc, v3, v2
	v_add_u32_e32 v3, 1, v5
	s_nop 0
	v_cndmask_b32_e32 v1, v1, v4, vcc
	v_mul_lo_u32 v4, v2, v1
	v_add_u32_e32 v2, v4, v2
	v_cmp_ne_u32_e32 vcc, v3, v2
	s_and_saveexec_b64 s[4:5], vcc
	s_xor_b64 s[8:9], exec, s[4:5]
	s_cbranch_execz .LBB0_153
	v_readlane_b32 s4, v245, 18
	s_waitcnt lgkmcnt(0)
	v_mov_b32_e32 v0, 0
	v_readlane_b32 s5, v245, 19
	s_nop 4
	global_load_dword v2, v0, s[4:5] sc1
	s_waitcnt vmcnt(0)
	v_cmp_eq_u32_e32 vcc, v2, v1
	s_and_saveexec_b64 s[14:15], vcc
	s_cbranch_execz .LBB0_152
	s_mov_b32 s3, 1
	s_mov_b64 s[18:19], 0
	s_branch .LBB0_143

; __device__ __forceinline__ unsigned xb_ld(unsigned* p)              { return __hip_atomic_load(p, __ATOMIC_RELAXED, __HIP_MEMORY_SCOPE_AGENT); }
; #define XB_SPIN(cond, bar) do { unsigned _sp = 0; while (cond) { __builtin_amdgcn_s_sleep(1); \
;     if ((++_sp & 255u) == 0u) { if (xb_ld(&(bar)[XB_TMO])) break; if (_sp > XB_SPIN_CAP) { atomicAdd(&(bar)[XB_TMO], 1u); break; } } } } while (0)
; __device__ __forceinline__ void xcd_barrier(const XcdBarrier& b) {
;     ...
;             XB_SPIN(xb_ld(&bar[XB_XGEN(b.x)]) == gen, bar);
;             __builtin_amdgcn_fence(__ATOMIC_ACQUIRE, "agent");
;             asm volatile("s_waitcnt vmcnt(0)" ::: "memory");
.LBB0_152:
	s_or_b64 exec, exec, s[14:15]
	s_waitcnt vmcnt(0)
	s_waitcnt vmcnt(0)

; __device__ __forceinline__ unsigned xb_ld(unsigned* p)              { return __hip_atomic_load(p, __ATOMIC_RELAXED, __HIP_MEMORY_SCOPE_AGENT); }
; __device__ __forceinline__ unsigned xb_add(unsigned* p, unsigned v) { return __hip_atomic_fetch_add(p, v, __ATOMIC_RELAXED, __HIP_MEMORY_SCOPE_AGENT); }
; #define XB_SPIN(cond, bar) do { unsigned _sp = 0; while (cond) { __builtin_amdgcn_s_sleep(1); \
;     if ((++_sp & 255u) == 0u) { if (xb_ld(&(bar)[XB_TMO])) break; if (_sp > XB_SPIN_CAP) { atomicAdd(&(bar)[XB_TMO], 1u); break; } } } } while (0)
; __device__ __forceinline__ void xcd_barrier(const XcdBarrier& b) {
;     ...
;             else XB_SPIN(xb_ld(&bar[XB_TOPGEN]) == tg, bar);
;             __builtin_amdgcn_fence(__ATOMIC_ACQUIRE, "agent");
;             xb_add(&bar[XB_XGEN(b.x)], 1u);
.LBB0_170:
	s_or_b64 exec, exec, s[8:9]
	s_mov_b64 s[8:9], exec
	v_mbcnt_lo_u32_b32 v0, s8, 0
	v_mbcnt_hi_u32_b32 v0, s9, v0
	v_cmp_eq_u32_e32 vcc, 0, v0
	s_waitcnt vmcnt(0)
	s_and_saveexec_b64 s[14:15], vcc
	s_cbranch_execz .LBB0_172
	s_bcnt1_i32_b64 s3, s[8:9]
	v_readlane_b32 s4, v245, 18
	v_mov_b32_e32 v0, 0
	v_mov_b32_e32 v1, s3
	v_readlane_b32 s5, v245, 19
	s_nop 4
	global_atomic_add v0, v1, s[4:5]

; __device__ __forceinline__ unsigned xb_ld(unsigned* p)              { return __hip_atomic_load(p, __ATOMIC_RELAXED, __HIP_MEMORY_SCOPE_AGENT); }
; __device__ __forceinline__ unsigned xb_add(unsigned* p, unsigned v) { return __hip_atomic_fetch_add(p, v, __ATOMIC_RELAXED, __HIP_MEMORY_SCOPE_AGENT); }
; #define XB_SPIN(cond, bar) do { unsigned _sp = 0; while (cond) { __builtin_amdgcn_s_sleep(1); \
;     if ((++_sp & 255u) == 0u) { if (xb_ld(&(bar)[XB_TMO])) break; if (_sp > XB_SPIN_CAP) { atomicAdd(&(bar)[XB_TMO], 1u); break; } } } } while (0)
; __device__ __forceinline__ void xcd_barrier(const XcdBarrier& b) {
;     ...
;         unsigned nloc = b.st[0], nx = b.st[1];
;         if (nloc == 0u) { xcd_barrier_complete(bar, b.x, nloc, nx); b.st[0] = nloc; b.st[1] = nx; }
;         const unsigned old = xb_add(&bar[XB_XSUB(b.x)], 1u);
;         const unsigned gen = old / nloc;
;         if (old + 1u == (gen + 1u) * nloc) {
;             __builtin_amdgcn_fence(__ATOMIC_RELEASE, "agent");
;             asm volatile("s_waitcnt vmcnt(0)" ::: "memory");
;             const unsigned og = xb_add(&bar[XB_TOP], 1u);
;             const unsigned tg = og / nx;
;             if (og + 1u == (tg + 1u) * nx) xb_add(&bar[XB_TOPGEN], 1u);
;             else XB_SPIN(xb_ld(&bar[XB_TOPGEN]) == tg, bar);
;             __builtin_amdgcn_fence(__ATOMIC_ACQUIRE, "agent");
;             xb_add(&bar[XB_XGEN(b.x)], 1u);
;             asm volatile("s_waitcnt vmcnt(0)" ::: "memory");
;         } else {
;             XB_SPIN(xb_ld(&bar[XB_XGEN(b.x)]) == gen, bar);
.LBB0_227:
	s_or_b64 exec, exec, s[16:17]
	buffer_wbl2 sc1
	buffer_inv sc1
	v_cvt_f32_u32_e32 v5, v3
	s_waitcnt vmcnt(2)
	v_readfirstlane_b32 s16, v4
	v_sub_u32_e32 v4, 0, v3
	v_rcp_iflag_f32_e32 v5, v5
	v_add_u32_e32 v6, s16, v0
	v_mul_f32_e32 v5, 0x4f7ffffe, v5
	v_cvt_u32_f32_e32 v5, v5
	v_mul_lo_u32 v0, v4, v5
	v_mul_hi_u32 v0, v5, v0
	v_add_u32_e32 v0, v5, v0
	v_mul_hi_u32 v0, v6, v0
	v_mul_lo_u32 v4, v0, v3
	v_sub_u32_e32 v4, v6, v4
	v_add_u32_e32 v5, 1, v0
	v_cmp_ge_u32_e32 vcc, v4, v3
	s_nop 1
	v_cndmask_b32_e32 v0, v0, v5, vcc
	v_sub_u32_e32 v5, v4, v3
	v_cndmask_b32_e32 v4, v4, v5, vcc
	v_add_u32_e32 v5, 1, v0
	v_cmp_ge_u32_e32 vcc, v4, v3
	v_add_u32_e32 v4, 1, v6
	s_nop 0
	v_cndmask_b32_e32 v0, v0, v5, vcc
	v_mul_lo_u32 v5, v3, v0
	v_add_u32_e32 v3, v5, v3
	v_cmp_ne_u32_e32 vcc, v4, v3
	s_and_saveexec_b64 s[16:17], vcc
	s_xor_b64 s[20:21], exec, s[16:17]
	s_cbranch_execz .LBB0_241
	v_readlane_b32 s16, v245, 18
	v_readlane_b32 s17, v245, 19
	s_waitcnt lgkmcnt(0)
	s_nop 3
	global_load_dword v2, v1, s[16:17] sc1
	s_waitcnt vmcnt(0)
	v_cmp_eq_u32_e32 vcc, v2, v0
	s_and_saveexec_b64 s[22:23], vcc
	s_cbranch_execz .LBB0_240
	s_mov_b32 s44, 1
	s_mov_b64 s[36:37], 0
	s_branch .LBB0_231

; __device__ __forceinline__ unsigned xb_ld(unsigned* p)              { return __hip_atomic_load(p, __ATOMIC_RELAXED, __HIP_MEMORY_SCOPE_AGENT); }
; #define XB_SPIN(cond, bar) do { unsigned _sp = 0; while (cond) { __builtin_amdgcn_s_sleep(1); \
;     if ((++_sp & 255u) == 0u) { if (xb_ld(&(bar)[XB_TMO])) break; if (_sp > XB_SPIN_CAP) { atomicAdd(&(bar)[XB_TMO], 1u); break; } } } } while (0)
; __device__ __forceinline__ void xcd_barrier(const XcdBarrier& b) {
;     ...
;             XB_SPIN(xb_ld(&bar[XB_XGEN(b.x)]) == gen, bar);
;             __builtin_amdgcn_fence(__ATOMIC_ACQUIRE, "agent");
;             asm volatile("s_waitcnt vmcnt(0)" ::: "memory");
.LBB0_240:
	s_or_b64 exec, exec, s[22:23]
	s_waitcnt vmcnt(0)
	s_waitcnt vmcnt(0)

; __device__ __forceinline__ unsigned xb_ld(unsigned* p)              { return __hip_atomic_load(p, __ATOMIC_RELAXED, __HIP_MEMORY_SCOPE_AGENT); }
; __device__ __forceinline__ unsigned xb_add(unsigned* p, unsigned v) { return __hip_atomic_fetch_add(p, v, __ATOMIC_RELAXED, __HIP_MEMORY_SCOPE_AGENT); }
; #define XB_SPIN(cond, bar) do { unsigned _sp = 0; while (cond) { __builtin_amdgcn_s_sleep(1); \
;     if ((++_sp & 255u) == 0u) { if (xb_ld(&(bar)[XB_TMO])) break; if (_sp > XB_SPIN_CAP) { atomicAdd(&(bar)[XB_TMO], 1u); break; } } } } while (0)
; __device__ __forceinline__ void xcd_barrier(const XcdBarrier& b) {
;     ...
;             else XB_SPIN(xb_ld(&bar[XB_TOPGEN]) == tg, bar);
;             __builtin_amdgcn_fence(__ATOMIC_ACQUIRE, "agent");
;             xb_add(&bar[XB_XGEN(b.x)], 1u);
.LBB0_258:
	s_or_b64 exec, exec, s[16:17]
	s_mov_b64 s[16:17], exec
	v_mbcnt_lo_u32_b32 v0, s16, 0
	v_mbcnt_hi_u32_b32 v0, s17, v0
	v_cmp_eq_u32_e32 vcc, 0, v0
	s_waitcnt vmcnt(0)
	s_and_saveexec_b64 s[20:21], vcc
	s_cbranch_execz .LBB0_260
	s_bcnt1_i32_b64 s16, s[16:17]
	v_mov_b32_e32 v0, s16
	v_readlane_b32 s16, v245, 18
	v_readlane_b32 s17, v245, 19
	s_nop 4
	global_atomic_add v1, v0, s[16:17]

; __device__ __forceinline__ unsigned xb_ld(unsigned* p)              { return __hip_atomic_load(p, __ATOMIC_RELAXED, __HIP_MEMORY_SCOPE_AGENT); }
; __device__ __forceinline__ unsigned xb_add(unsigned* p, unsigned v) { return __hip_atomic_fetch_add(p, v, __ATOMIC_RELAXED, __HIP_MEMORY_SCOPE_AGENT); }
; #define XB_SPIN(cond, bar) do { unsigned _sp = 0; while (cond) { __builtin_amdgcn_s_sleep(1); \
;     if ((++_sp & 255u) == 0u) { if (xb_ld(&(bar)[XB_TMO])) break; if (_sp > XB_SPIN_CAP) { atomicAdd(&(bar)[XB_TMO], 1u); break; } } } } while (0)
; __device__ __forceinline__ void xcd_barrier(const XcdBarrier& b) {
;     ...
;         unsigned nloc = b.st[0], nx = b.st[1];
;         if (nloc == 0u) { xcd_barrier_complete(bar, b.x, nloc, nx); b.st[0] = nloc; b.st[1] = nx; }
;         const unsigned old = xb_add(&bar[XB_XSUB(b.x)], 1u);
;         const unsigned gen = old / nloc;
;         if (old + 1u == (gen + 1u) * nloc) {
;             __builtin_amdgcn_fence(__ATOMIC_RELEASE, "agent");
;             asm volatile("s_waitcnt vmcnt(0)" ::: "memory");
;             const unsigned og = xb_add(&bar[XB_TOP], 1u);
;             const unsigned tg = og / nx;
;             if (og + 1u == (tg + 1u) * nx) xb_add(&bar[XB_TOPGEN], 1u);
;             else XB_SPIN(xb_ld(&bar[XB_TOPGEN]) == tg, bar);
;             __builtin_amdgcn_fence(__ATOMIC_ACQUIRE, "agent");
;             xb_add(&bar[XB_XGEN(b.x)], 1u);
;             asm volatile("s_waitcnt vmcnt(0)" ::: "memory");
;         } else {
;             XB_SPIN(xb_ld(&bar[XB_XGEN(b.x)]) == gen, bar);
.LBB0_396:
	s_or_b64 exec, exec, s[16:17]
	buffer_wbl2 sc1
	buffer_inv sc1
	v_cvt_f32_u32_e32 v5, v3
	s_waitcnt vmcnt(2)
	v_readfirstlane_b32 s16, v4
	v_sub_u32_e32 v4, 0, v3
	v_rcp_iflag_f32_e32 v5, v5
	v_add_u32_e32 v6, s16, v0
	v_mul_f32_e32 v5, 0x4f7ffffe, v5
	v_cvt_u32_f32_e32 v5, v5
	v_mul_lo_u32 v0, v4, v5
	v_mul_hi_u32 v0, v5, v0
	v_add_u32_e32 v0, v5, v0
	v_mul_hi_u32 v0, v6, v0
	v_mul_lo_u32 v4, v0, v3
	v_sub_u32_e32 v4, v6, v4
	v_add_u32_e32 v5, 1, v0
	v_cmp_ge_u32_e32 vcc, v4, v3
	s_nop 1
	v_cndmask_b32_e32 v0, v0, v5, vcc
	v_sub_u32_e32 v5, v4, v3
	v_cndmask_b32_e32 v4, v4, v5, vcc
	v_add_u32_e32 v5, 1, v0
	v_cmp_ge_u32_e32 vcc, v4, v3
	v_add_u32_e32 v4, 1, v6
	s_nop 0
	v_cndmask_b32_e32 v0, v0, v5, vcc
	v_mul_lo_u32 v5, v3, v0
	v_add_u32_e32 v3, v5, v3
	v_cmp_ne_u32_e32 vcc, v4, v3
	s_and_saveexec_b64 s[16:17], vcc
	s_xor_b64 s[36:37], exec, s[16:17]
	s_cbranch_execz .LBB0_410
	v_readlane_b32 s16, v245, 18
	v_readlane_b32 s17, v245, 19
	s_waitcnt lgkmcnt(0)
	s_nop 3
	global_load_dword v2, v1, s[16:17] sc1
	s_waitcnt vmcnt(0)
	v_cmp_eq_u32_e32 vcc, v2, v0
	s_and_saveexec_b64 s[38:39], vcc
	s_cbranch_execz .LBB0_409
	s_mov_b32 s23, 1
	s_mov_b64 s[40:41], 0
	s_branch .LBB0_400

; __device__ __forceinline__ unsigned xb_ld(unsigned* p)              { return __hip_atomic_load(p, __ATOMIC_RELAXED, __HIP_MEMORY_SCOPE_AGENT); }
; #define XB_SPIN(cond, bar) do { unsigned _sp = 0; while (cond) { __builtin_amdgcn_s_sleep(1); \
;     if ((++_sp & 255u) == 0u) { if (xb_ld(&(bar)[XB_TMO])) break; if (_sp > XB_SPIN_CAP) { atomicAdd(&(bar)[XB_TMO], 1u); break; } } } } while (0)
; __device__ __forceinline__ void xcd_barrier(const XcdBarrier& b) {
;     ...
;             XB_SPIN(xb_ld(&bar[XB_XGEN(b.x)]) == gen, bar);
;             __builtin_amdgcn_fence(__ATOMIC_ACQUIRE, "agent");
;             asm volatile("s_waitcnt vmcnt(0)" ::: "memory");
.LBB0_409:
	s_or_b64 exec, exec, s[38:39]
	s_waitcnt vmcnt(0)
	s_waitcnt vmcnt(0)

; __device__ __forceinline__ unsigned xb_ld(unsigned* p)              { return __hip_atomic_load(p, __ATOMIC_RELAXED, __HIP_MEMORY_SCOPE_AGENT); }
; __device__ __forceinline__ unsigned xb_add(unsigned* p, unsigned v) { return __hip_atomic_fetch_add(p, v, __ATOMIC_RELAXED, __HIP_MEMORY_SCOPE_AGENT); }
; #define XB_SPIN(cond, bar) do { unsigned _sp = 0; while (cond) { __builtin_amdgcn_s_sleep(1); \
;     if ((++_sp & 255u) == 0u) { if (xb_ld(&(bar)[XB_TMO])) break; if (_sp > XB_SPIN_CAP) { atomicAdd(&(bar)[XB_TMO], 1u); break; } } } } while (0)
; __device__ __forceinline__ void xcd_barrier(const XcdBarrier& b) {
;     ...
;             else XB_SPIN(xb_ld(&bar[XB_TOPGEN]) == tg, bar);
;             __builtin_amdgcn_fence(__ATOMIC_ACQUIRE, "agent");
;             xb_add(&bar[XB_XGEN(b.x)], 1u);
.LBB0_427:
	s_or_b64 exec, exec, s[16:17]
	s_mov_b64 s[16:17], exec
	v_mbcnt_lo_u32_b32 v0, s16, 0
	v_mbcnt_hi_u32_b32 v0, s17, v0
	v_cmp_eq_u32_e32 vcc, 0, v0
	s_waitcnt vmcnt(0)
	s_and_saveexec_b64 s[36:37], vcc
	s_cbranch_execz .LBB0_429
	s_bcnt1_i32_b64 s16, s[16:17]
	v_mov_b32_e32 v0, s16
	v_readlane_b32 s16, v245, 18
	v_readlane_b32 s17, v245, 19
	s_nop 4
	global_atomic_add v1, v0, s[16:17]

; __device__ __forceinline__ unsigned xb_ld(unsigned* p)              { return __hip_atomic_load(p, __ATOMIC_RELAXED, __HIP_MEMORY_SCOPE_AGENT); }
; __device__ __forceinline__ unsigned xb_add(unsigned* p, unsigned v) { return __hip_atomic_fetch_add(p, v, __ATOMIC_RELAXED, __HIP_MEMORY_SCOPE_AGENT); }
; #define XB_SPIN(cond, bar) do { unsigned _sp = 0; while (cond) { __builtin_amdgcn_s_sleep(1); \
;     if ((++_sp & 255u) == 0u) { if (xb_ld(&(bar)[XB_TMO])) break; if (_sp > XB_SPIN_CAP) { atomicAdd(&(bar)[XB_TMO], 1u); break; } } } } while (0)
; __device__ __forceinline__ void xcd_barrier(const XcdBarrier& b) {
;     ...
;         unsigned nloc = b.st[0], nx = b.st[1];
;         if (nloc == 0u) { xcd_barrier_complete(bar, b.x, nloc, nx); b.st[0] = nloc; b.st[1] = nx; }
;         const unsigned old = xb_add(&bar[XB_XSUB(b.x)], 1u);
;         const unsigned gen = old / nloc;
;         if (old + 1u == (gen + 1u) * nloc) {
;             __builtin_amdgcn_fence(__ATOMIC_RELEASE, "agent");
;             asm volatile("s_waitcnt vmcnt(0)" ::: "memory");
;             const unsigned og = xb_add(&bar[XB_TOP], 1u);
;             const unsigned tg = og / nx;
;             if (og + 1u == (tg + 1u) * nx) xb_add(&bar[XB_TOPGEN], 1u);
;             else XB_SPIN(xb_ld(&bar[XB_TOPGEN]) == tg, bar);
;             __builtin_amdgcn_fence(__ATOMIC_ACQUIRE, "agent");
;             xb_add(&bar[XB_XGEN(b.x)], 1u);
;             asm volatile("s_waitcnt vmcnt(0)" ::: "memory");
;         } else {
;             XB_SPIN(xb_ld(&bar[XB_XGEN(b.x)]) == gen, bar);
.LBB0_537:
	s_or_b64 exec, exec, s[16:17]
	buffer_wbl2 sc1
	buffer_inv sc1
	v_cvt_f32_u32_e32 v5, v3
	s_waitcnt vmcnt(2)
	v_readfirstlane_b32 s16, v4
	v_sub_u32_e32 v4, 0, v3
	v_rcp_iflag_f32_e32 v5, v5
	v_add_u32_e32 v6, s16, v0
	v_mul_f32_e32 v5, 0x4f7ffffe, v5
	v_cvt_u32_f32_e32 v5, v5
	v_mul_lo_u32 v0, v4, v5
	v_mul_hi_u32 v0, v5, v0
	v_add_u32_e32 v0, v5, v0
	v_mul_hi_u32 v0, v6, v0
	v_mul_lo_u32 v4, v0, v3
	v_sub_u32_e32 v4, v6, v4
	v_add_u32_e32 v5, 1, v0
	v_cmp_ge_u32_e32 vcc, v4, v3
	s_nop 1
	v_cndmask_b32_e32 v0, v0, v5, vcc
	v_sub_u32_e32 v5, v4, v3
	v_cndmask_b32_e32 v4, v4, v5, vcc
	v_add_u32_e32 v5, 1, v0
	v_cmp_ge_u32_e32 vcc, v4, v3
	v_add_u32_e32 v4, 1, v6
	s_nop 0
	v_cndmask_b32_e32 v0, v0, v5, vcc
	v_mul_lo_u32 v5, v3, v0
	v_add_u32_e32 v3, v5, v3
	v_cmp_ne_u32_e32 vcc, v4, v3
	s_and_saveexec_b64 s[16:17], vcc
	s_xor_b64 s[36:37], exec, s[16:17]
	s_cbranch_execz .LBB0_551
	v_readlane_b32 s16, v245, 18
	v_readlane_b32 s17, v245, 19
	s_waitcnt lgkmcnt(0)
	s_nop 3
	global_load_dword v2, v1, s[16:17] sc1
	s_waitcnt vmcnt(0)
	v_cmp_eq_u32_e32 vcc, v2, v0
	s_and_saveexec_b64 s[40:41], vcc
	s_cbranch_execz .LBB0_550
	s_mov_b32 s23, 1
	s_mov_b64 s[42:43], 0
	s_branch .LBB0_541

; __device__ __forceinline__ unsigned xb_ld(unsigned* p)              { return __hip_atomic_load(p, __ATOMIC_RELAXED, __HIP_MEMORY_SCOPE_AGENT); }
; #define XB_SPIN(cond, bar) do { unsigned _sp = 0; while (cond) { __builtin_amdgcn_s_sleep(1); \
;     if ((++_sp & 255u) == 0u) { if (xb_ld(&(bar)[XB_TMO])) break; if (_sp > XB_SPIN_CAP) { atomicAdd(&(bar)[XB_TMO], 1u); break; } } } } while (0)
; __device__ __forceinline__ void xcd_barrier(const XcdBarrier& b) {
;     ...
;             XB_SPIN(xb_ld(&bar[XB_XGEN(b.x)]) == gen, bar);
;             __builtin_amdgcn_fence(__ATOMIC_ACQUIRE, "agent");
;             asm volatile("s_waitcnt vmcnt(0)" ::: "memory");
.LBB0_550:
	s_or_b64 exec, exec, s[40:41]
	s_waitcnt vmcnt(0)
	s_waitcnt vmcnt(0)

; __device__ __forceinline__ unsigned xb_ld(unsigned* p)              { return __hip_atomic_load(p, __ATOMIC_RELAXED, __HIP_MEMORY_SCOPE_AGENT); }
; __device__ __forceinline__ unsigned xb_add(unsigned* p, unsigned v) { return __hip_atomic_fetch_add(p, v, __ATOMIC_RELAXED, __HIP_MEMORY_SCOPE_AGENT); }
; #define XB_SPIN(cond, bar) do { unsigned _sp = 0; while (cond) { __builtin_amdgcn_s_sleep(1); \
;     if ((++_sp & 255u) == 0u) { if (xb_ld(&(bar)[XB_TMO])) break; if (_sp > XB_SPIN_CAP) { atomicAdd(&(bar)[XB_TMO], 1u); break; } } } } while (0)
; __device__ __forceinline__ void xcd_barrier(const XcdBarrier& b) {
;     ...
;         unsigned nloc = b.st[0], nx = b.st[1];
;         if (nloc == 0u) { xcd_barrier_complete(bar, b.x, nloc, nx); b.st[0] = nloc; b.st[1] = nx; }
;         const unsigned old = xb_add(&bar[XB_XSUB(b.x)], 1u);
;         const unsigned gen = old / nloc;
;         if (old + 1u == (gen + 1u) * nloc) {
;             __builtin_amdgcn_fence(__ATOMIC_RELEASE, "agent");
;             asm volatile("s_waitcnt vmcnt(0)" ::: "memory");
;             const unsigned og = xb_add(&bar[XB_TOP], 1u);
;             const unsigned tg = og / nx;
;             if (og + 1u == (tg + 1u) * nx) xb_add(&bar[XB_TOPGEN], 1u);
;             else XB_SPIN(xb_ld(&bar[XB_TOPGEN]) == tg, bar);
;             __builtin_amdgcn_fence(__ATOMIC_ACQUIRE, "agent");
;             xb_add(&bar[XB_XGEN(b.x)], 1u);
;             asm volatile("s_waitcnt vmcnt(0)" ::: "memory");
;         } else {
;             XB_SPIN(xb_ld(&bar[XB_XGEN(b.x)]) == gen, bar);
.LBB0_752:
	s_or_b64 exec, exec, s[16:17]
	buffer_wbl2 sc1
	buffer_inv sc1
	v_cvt_f32_u32_e32 v5, v3
	s_waitcnt vmcnt(2)
	v_readfirstlane_b32 s16, v4
	v_sub_u32_e32 v4, 0, v3
	v_rcp_iflag_f32_e32 v5, v5
	v_add_u32_e32 v6, s16, v0
	v_mul_f32_e32 v5, 0x4f7ffffe, v5
	v_cvt_u32_f32_e32 v5, v5
	v_mul_lo_u32 v0, v4, v5
	v_mul_hi_u32 v0, v5, v0
	v_add_u32_e32 v0, v5, v0
	v_mul_hi_u32 v0, v6, v0
	v_mul_lo_u32 v4, v0, v3
	v_sub_u32_e32 v4, v6, v4
	v_add_u32_e32 v5, 1, v0
	v_cmp_ge_u32_e32 vcc, v4, v3
	s_nop 1
	v_cndmask_b32_e32 v0, v0, v5, vcc
	v_sub_u32_e32 v5, v4, v3
	v_cndmask_b32_e32 v4, v4, v5, vcc
	v_add_u32_e32 v5, 1, v0
	v_cmp_ge_u32_e32 vcc, v4, v3
	v_add_u32_e32 v4, 1, v6
	s_nop 0
	v_cndmask_b32_e32 v0, v0, v5, vcc
	v_mul_lo_u32 v5, v3, v0
	v_add_u32_e32 v3, v5, v3
	v_cmp_ne_u32_e32 vcc, v4, v3
	s_and_saveexec_b64 s[16:17], vcc
	s_xor_b64 s[18:19], exec, s[16:17]
	s_cbranch_execz .LBB0_766
	v_readlane_b32 s16, v245, 18
	v_readlane_b32 s17, v245, 19
	s_waitcnt lgkmcnt(0)
	s_nop 3
	global_load_dword v2, v1, s[16:17] sc1
	s_waitcnt vmcnt(0)
	v_cmp_eq_u32_e32 vcc, v2, v0
	s_and_saveexec_b64 s[20:21], vcc
	s_cbranch_execz .LBB0_765
	s_mov_b32 s42, 1
	s_mov_b64 s[22:23], 0
	s_branch .LBB0_756

; __device__ __forceinline__ unsigned xb_ld(unsigned* p)              { return __hip_atomic_load(p, __ATOMIC_RELAXED, __HIP_MEMORY_SCOPE_AGENT); }
; #define XB_SPIN(cond, bar) do { unsigned _sp = 0; while (cond) { __builtin_amdgcn_s_sleep(1); \
;     if ((++_sp & 255u) == 0u) { if (xb_ld(&(bar)[XB_TMO])) break; if (_sp > XB_SPIN_CAP) { atomicAdd(&(bar)[XB_TMO], 1u); break; } } } } while (0)
; __device__ __forceinline__ void xcd_barrier(const XcdBarrier& b) {
;     ...
;             XB_SPIN(xb_ld(&bar[XB_XGEN(b.x)]) == gen, bar);
;             __builtin_amdgcn_fence(__ATOMIC_ACQUIRE, "agent");
;             asm volatile("s_waitcnt vmcnt(0)" ::: "memory");
.LBB0_765:
	s_or_b64 exec, exec, s[20:21]
	s_waitcnt vmcnt(0)
	s_waitcnt vmcnt(0)

; __device__ __forceinline__ unsigned xb_ld(unsigned* p)              { return __hip_atomic_load(p, __ATOMIC_RELAXED, __HIP_MEMORY_SCOPE_AGENT); }
; __device__ __forceinline__ unsigned xb_add(unsigned* p, unsigned v) { return __hip_atomic_fetch_add(p, v, __ATOMIC_RELAXED, __HIP_MEMORY_SCOPE_AGENT); }
; #define XB_SPIN(cond, bar) do { unsigned _sp = 0; while (cond) { __builtin_amdgcn_s_sleep(1); \
;     if ((++_sp & 255u) == 0u) { if (xb_ld(&(bar)[XB_TMO])) break; if (_sp > XB_SPIN_CAP) { atomicAdd(&(bar)[XB_TMO], 1u); break; } } } } while (0)
; __device__ __forceinline__ void xcd_barrier(const XcdBarrier& b) {
;     ...
;             else XB_SPIN(xb_ld(&bar[XB_TOPGEN]) == tg, bar);
;             __builtin_amdgcn_fence(__ATOMIC_ACQUIRE, "agent");
;             xb_add(&bar[XB_XGEN(b.x)], 1u);
.LBB0_783:
	s_or_b64 exec, exec, s[16:17]
	s_mov_b64 s[16:17], exec
	v_mbcnt_lo_u32_b32 v0, s16, 0
	v_mbcnt_hi_u32_b32 v0, s17, v0
	v_cmp_eq_u32_e32 vcc, 0, v0
	s_waitcnt vmcnt(0)
	s_and_saveexec_b64 s[18:19], vcc
	s_cbranch_execz .LBB0_174
	s_bcnt1_i32_b64 s16, s[16:17]
	v_mov_b32_e32 v0, s16
	v_readlane_b32 s16, v245, 18
	v_readlane_b32 s17, v245, 19
	s_nop 4
	global_atomic_add v1, v0, s[16:17]
	s_branch .LBB0_174
